# scan recurrence loop: first pair of a chunk starts as soon as its a1/aw vectors are in, the second pair's loads are issued behind its first six instructions
# baseline (speedup 1.0000x reference)
.LBB0_1112:
	s_and_b32 s11, s10, 1
	s_mul_i32 s18, s11, 0x4e00
	s_waitcnt vmcnt(0)
	v_lshl_add_u32 v131, s11, 14, v21
	v_lshl_add_u32 v130, v20, 2, s18
	v_mov_b32_e32 v129, s18
	v_lshl_add_u32 v128, v16, 2, s18
	s_add_i32 s10, s10, 1
	ds_read_b128 v[44:47], v130 offset:0
	ds_read_b128 v[48:51], v130 offset:256
	ds_read_b128 v[52:55], v130 offset:512
	ds_read_b128 v[56:59], v130 offset:768
	ds_read_b128 v[60:63], v130 offset:1024
	ds_read_b128 v[64:67], v130 offset:1280
	ds_read_b128 v[68:71], v130 offset:1536
	ds_read_b128 v[72:75], v130 offset:1792
	ds_read_b128 v[76:79], v130 offset:2048
	ds_read_b128 v[80:83], v129 offset:2432
	ds_read_b128 v[84:87], v129 offset:2448
	ds_read_b32 v89, v128 offset:2304
	ds_read_b32 v91, v128 offset:2368
	s_waitcnt lgkmcnt(11)
	v_pk_mul_f32 v[4:5], v[0:1], v[44:45]
	v_pk_mul_f32 v[6:7], v[0:1], v[48:49]
	v_pk_fma_f32 v[4:5], v[2:3], v[46:47], v[4:5]
	v_pk_fma_f32 v[6:7], v[2:3], v[50:51], v[6:7]
	v_add_f32_e32 v22, v4, v5
	v_add_f32_e32 v42, v6, v7
	ds_read_b128 v[196:199], v130 offset:2496
	ds_read_b128 v[200:203], v130 offset:2752
	ds_read_b128 v[204:207], v130 offset:3008
	ds_read_b128 v[208:211], v130 offset:3264
	ds_read_b128 v[212:215], v130 offset:3520
	ds_read_b128 v[216:219], v130 offset:3776
	ds_read_b128 v[220:223], v130 offset:4032
	ds_read_b128 v[224:227], v130 offset:4288
	ds_read_b128 v[228:231], v130 offset:4544
	ds_read_b128 v[232:235], v129 offset:4928
	ds_read_b128 v[236:239], v129 offset:4944
	ds_read_b32 v241, v128 offset:4800
	ds_read_b32 v243, v128 offset:4864
	s_waitcnt lgkmcnt(13)
	v_pk_mul_f32 v[8:9], v[0:1], v[52:53]
	v_add_f32_dpp v22, v22, v22 quad_perm:[1,0,3,2] row_mask:0xf bank_mask:0xf bound_ctrl:1
	v_add_f32_dpp v42, v42, v42 quad_perm:[1,0,3,2] row_mask:0xf bank_mask:0xf bound_ctrl:1
	v_pk_mul_f32 v[10:11], v[2:3], v[54:55]
	v_add_f32_dpp v22, v22, v22 quad_perm:[2,3,0,1] row_mask:0xf bank_mask:0xf bound_ctrl:1
	v_add_f32_dpp v42, v42, v42 quad_perm:[2,3,0,1] row_mask:0xf bank_mask:0xf bound_ctrl:1
	v_pk_mul_f32 v[12:13], v[0:1], v[72:73]
	v_add_f32_dpp v22, v22, v22 row_ror:4 row_mask:0xf bank_mask:0xf bound_ctrl:1
	v_add_f32_dpp v42, v42, v42 row_ror:4 row_mask:0xf bank_mask:0xf bound_ctrl:1
	v_pk_mul_f32 v[14:15], v[0:1], v[76:77]
	v_add_f32_dpp v88, v22, v22 row_ror:8 row_mask:0xf bank_mask:0xf bound_ctrl:1
	v_add_f32_dpp v42, v42, v42 row_ror:8 row_mask:0xf bank_mask:0xf bound_ctrl:1
	v_pk_fma_f32 v[8:9], v[88:89], v[60:61], v[8:9] op_sel:[1,0,0] op_sel_hi:[1,1,1]
	v_pk_fma_f32 v[10:11], v[88:89], v[62:63], v[10:11] op_sel:[1,0,0] op_sel_hi:[1,1,1]
	v_fma_f32 v4, v88, v80, v42
	v_pk_fma_f32 v[8:9], v[90:91], v[68:69], v[8:9] op_sel:[1,0,0] op_sel_hi:[1,1,1]
	v_fma_f32 v90, v89, v81, v4
	v_pk_fma_f32 v[10:11], v[90:91], v[70:71], v[10:11] op_sel:[1,0,0] op_sel_hi:[1,1,1]
	v_pk_fma_f32 v[12:13], v[2:3], v[74:75], v[12:13]
	v_pk_fma_f32 v[14:15], v[2:3], v[78:79], v[14:15]
	v_pk_fma_f32 v[0:1], v[88:89], v[56:57], v[8:9] op_sel:[0,0,0] op_sel_hi:[0,1,1]
	v_pk_fma_f32 v[2:3], v[88:89], v[58:59], v[10:11] op_sel:[0,0,0] op_sel_hi:[0,1,1]
	v_pk_fma_f32 v[0:1], v[90:91], v[64:65], v[0:1] op_sel:[0,0,0] op_sel_hi:[0,1,1]
	v_pk_fma_f32 v[2:3], v[90:91], v[66:67], v[2:3] op_sel:[0,0,0] op_sel_hi:[0,1,1]
	v_pk_fma_f32 v[12:13], v[88:89], v[82:83], v[12:13]
	v_pk_fma_f32 v[14:15], v[90:91], v[86:87], v[14:15]
	v_pk_fma_f32 v[14:15], v[88:89], v[84:85], v[14:15]
	v_add_f32_e32 v126, v12, v13
	v_add_f32_e32 v127, v14, v15
	ds_read_b128 v[44:47], v130 offset:4992
	ds_read_b128 v[48:51], v130 offset:5248
	ds_read_b128 v[52:55], v130 offset:5504
	ds_read_b128 v[56:59], v130 offset:5760
	ds_read_b128 v[60:63], v130 offset:6016
	ds_read_b128 v[64:67], v130 offset:6272
	ds_read_b128 v[68:71], v130 offset:6528
	ds_read_b128 v[72:75], v130 offset:6784
	ds_read_b128 v[76:79], v130 offset:7040
	ds_read_b128 v[80:83], v129 offset:7424
	ds_read_b128 v[84:87], v129 offset:7440
	ds_read_b32 v89, v128 offset:7296
	ds_read_b32 v91, v128 offset:7360
	ds_write2st64_b32 v131, v126, v127 offset0:156 offset1:160
	s_waitcnt lgkmcnt(14)
	v_pk_mul_f32 v[4:5], v[0:1], v[196:197]
	v_pk_mul_f32 v[6:7], v[0:1], v[200:201]
	v_pk_fma_f32 v[4:5], v[2:3], v[198:199], v[4:5]
	v_pk_fma_f32 v[6:7], v[2:3], v[202:203], v[6:7]
	v_add_f32_e32 v22, v4, v5
	v_add_f32_e32 v42, v6, v7
	v_pk_mul_f32 v[8:9], v[0:1], v[204:205]
	v_add_f32_dpp v22, v22, v22 quad_perm:[1,0,3,2] row_mask:0xf bank_mask:0xf bound_ctrl:1
	v_add_f32_dpp v42, v42, v42 quad_perm:[1,0,3,2] row_mask:0xf bank_mask:0xf bound_ctrl:1
	v_pk_mul_f32 v[10:11], v[2:3], v[206:207]
	v_add_f32_dpp v22, v22, v22 quad_perm:[2,3,0,1] row_mask:0xf bank_mask:0xf bound_ctrl:1
	v_add_f32_dpp v42, v42, v42 quad_perm:[2,3,0,1] row_mask:0xf bank_mask:0xf bound_ctrl:1
	v_pk_mul_f32 v[12:13], v[0:1], v[224:225]
	v_add_f32_dpp v22, v22, v22 row_ror:4 row_mask:0xf bank_mask:0xf bound_ctrl:1
	v_add_f32_dpp v42, v42, v42 row_ror:4 row_mask:0xf bank_mask:0xf bound_ctrl:1
	v_pk_mul_f32 v[14:15], v[0:1], v[228:229]
	v_add_f32_dpp v240, v22, v22 row_ror:8 row_mask:0xf bank_mask:0xf bound_ctrl:1
	v_add_f32_dpp v42, v42, v42 row_ror:8 row_mask:0xf bank_mask:0xf bound_ctrl:1
	v_pk_fma_f32 v[8:9], v[240:241], v[212:213], v[8:9] op_sel:[1,0,0] op_sel_hi:[1,1,1]
	v_pk_fma_f32 v[10:11], v[240:241], v[214:215], v[10:11] op_sel:[1,0,0] op_sel_hi:[1,1,1]
	v_fma_f32 v4, v240, v232, v42
	v_pk_fma_f32 v[8:9], v[242:243], v[220:221], v[8:9] op_sel:[1,0,0] op_sel_hi:[1,1,1]
	v_fma_f32 v242, v241, v233, v4
	v_pk_fma_f32 v[10:11], v[242:243], v[222:223], v[10:11] op_sel:[1,0,0] op_sel_hi:[1,1,1]
	v_pk_fma_f32 v[12:13], v[2:3], v[226:227], v[12:13]
	v_pk_fma_f32 v[14:15], v[2:3], v[230:231], v[14:15]
	v_pk_fma_f32 v[0:1], v[240:241], v[208:209], v[8:9] op_sel:[0,0,0] op_sel_hi:[0,1,1]
	v_pk_fma_f32 v[2:3], v[240:241], v[210:211], v[10:11] op_sel:[0,0,0] op_sel_hi:[0,1,1]
	v_pk_fma_f32 v[0:1], v[242:243], v[216:217], v[0:1] op_sel:[0,0,0] op_sel_hi:[0,1,1]
	v_pk_fma_f32 v[2:3], v[242:243], v[218:219], v[2:3] op_sel:[0,0,0] op_sel_hi:[0,1,1]
	v_pk_fma_f32 v[12:13], v[240:241], v[234:235], v[12:13]
	v_pk_fma_f32 v[14:15], v[242:243], v[238:239], v[14:15]
	v_pk_fma_f32 v[14:15], v[240:241], v[236:237], v[14:15]
	v_add_f32_e32 v126, v12, v13
	v_add_f32_e32 v127, v14, v15
	ds_read_b128 v[196:199], v130 offset:7488
	ds_read_b128 v[200:203], v130 offset:7744
	ds_read_b128 v[204:207], v130 offset:8000
	ds_read_b128 v[208:211], v130 offset:8256
	ds_read_b128 v[212:215], v130 offset:8512
	ds_read_b128 v[216:219], v130 offset:8768
	ds_read_b128 v[220:223], v130 offset:9024
	ds_read_b128 v[224:227], v130 offset:9280
	ds_read_b128 v[228:231], v130 offset:9536
	ds_read_b128 v[232:235], v129 offset:9920
	ds_read_b128 v[236:239], v129 offset:9936
	ds_read_b32 v241, v128 offset:9792
	ds_read_b32 v243, v128 offset:9856
	ds_write2st64_b32 v131, v126, v127 offset0:164 offset1:168
	s_waitcnt lgkmcnt(14)
	v_pk_mul_f32 v[4:5], v[0:1], v[44:45]
	v_pk_mul_f32 v[6:7], v[0:1], v[48:49]
	v_pk_fma_f32 v[4:5], v[2:3], v[46:47], v[4:5]
	v_pk_fma_f32 v[6:7], v[2:3], v[50:51], v[6:7]
	v_add_f32_e32 v22, v4, v5
	v_add_f32_e32 v42, v6, v7
	v_pk_mul_f32 v[8:9], v[0:1], v[52:53]
	v_add_f32_dpp v22, v22, v22 quad_perm:[1,0,3,2] row_mask:0xf bank_mask:0xf bound_ctrl:1
	v_add_f32_dpp v42, v42, v42 quad_perm:[1,0,3,2] row_mask:0xf bank_mask:0xf bound_ctrl:1
	v_pk_mul_f32 v[10:11], v[2:3], v[54:55]
	v_add_f32_dpp v22, v22, v22 quad_perm:[2,3,0,1] row_mask:0xf bank_mask:0xf bound_ctrl:1
	v_add_f32_dpp v42, v42, v42 quad_perm:[2,3,0,1] row_mask:0xf bank_mask:0xf bound_ctrl:1
	v_pk_mul_f32 v[12:13], v[0:1], v[72:73]
	v_add_f32_dpp v22, v22, v22 row_ror:4 row_mask:0xf bank_mask:0xf bound_ctrl:1
	v_add_f32_dpp v42, v42, v42 row_ror:4 row_mask:0xf bank_mask:0xf bound_ctrl:1
	v_pk_mul_f32 v[14:15], v[0:1], v[76:77]
	v_add_f32_dpp v88, v22, v22 row_ror:8 row_mask:0xf bank_mask:0xf bound_ctrl:1
	v_add_f32_dpp v42, v42, v42 row_ror:8 row_mask:0xf bank_mask:0xf bound_ctrl:1
	v_pk_fma_f32 v[8:9], v[88:89], v[60:61], v[8:9] op_sel:[1,0,0] op_sel_hi:[1,1,1]
	v_pk_fma_f32 v[10:11], v[88:89], v[62:63], v[10:11] op_sel:[1,0,0] op_sel_hi:[1,1,1]
	v_fma_f32 v4, v88, v80, v42
	v_pk_fma_f32 v[8:9], v[90:91], v[68:69], v[8:9] op_sel:[1,0,0] op_sel_hi:[1,1,1]
	v_fma_f32 v90, v89, v81, v4
	v_pk_fma_f32 v[10:11], v[90:91], v[70:71], v[10:11] op_sel:[1,0,0] op_sel_hi:[1,1,1]
	v_pk_fma_f32 v[12:13], v[2:3], v[74:75], v[12:13]
	v_pk_fma_f32 v[14:15], v[2:3], v[78:79], v[14:15]
	v_pk_fma_f32 v[0:1], v[88:89], v[56:57], v[8:9] op_sel:[0,0,0] op_sel_hi:[0,1,1]
	v_pk_fma_f32 v[2:3], v[88:89], v[58:59], v[10:11] op_sel:[0,0,0] op_sel_hi:[0,1,1]
	v_pk_fma_f32 v[0:1], v[90:91], v[64:65], v[0:1] op_sel:[0,0,0] op_sel_hi:[0,1,1]
	v_pk_fma_f32 v[2:3], v[90:91], v[66:67], v[2:3] op_sel:[0,0,0] op_sel_hi:[0,1,1]
	v_pk_fma_f32 v[12:13], v[88:89], v[82:83], v[12:13]
	v_pk_fma_f32 v[14:15], v[90:91], v[86:87], v[14:15]
	v_pk_fma_f32 v[14:15], v[88:89], v[84:85], v[14:15]
	v_add_f32_e32 v126, v12, v13
	v_add_f32_e32 v127, v14, v15
	ds_read_b128 v[44:47], v130 offset:9984
	ds_read_b128 v[48:51], v130 offset:10240
	ds_read_b128 v[52:55], v130 offset:10496
	ds_read_b128 v[56:59], v130 offset:10752
	ds_read_b128 v[60:63], v130 offset:11008
	ds_read_b128 v[64:67], v130 offset:11264
	ds_read_b128 v[68:71], v130 offset:11520
	ds_read_b128 v[72:75], v130 offset:11776
	ds_read_b128 v[76:79], v130 offset:12032
	ds_read_b128 v[80:83], v129 offset:12416
	ds_read_b128 v[84:87], v129 offset:12432
	ds_read_b32 v89, v128 offset:12288
	ds_read_b32 v91, v128 offset:12352
	ds_write2st64_b32 v131, v126, v127 offset0:172 offset1:176
	s_waitcnt lgkmcnt(14)
	v_pk_mul_f32 v[4:5], v[0:1], v[196:197]
	v_pk_mul_f32 v[6:7], v[0:1], v[200:201]
	v_pk_fma_f32 v[4:5], v[2:3], v[198:199], v[4:5]
	v_pk_fma_f32 v[6:7], v[2:3], v[202:203], v[6:7]
	v_add_f32_e32 v22, v4, v5
	v_add_f32_e32 v42, v6, v7
	v_pk_mul_f32 v[8:9], v[0:1], v[204:205]
	v_add_f32_dpp v22, v22, v22 quad_perm:[1,0,3,2] row_mask:0xf bank_mask:0xf bound_ctrl:1
	v_add_f32_dpp v42, v42, v42 quad_perm:[1,0,3,2] row_mask:0xf bank_mask:0xf bound_ctrl:1
	v_pk_mul_f32 v[10:11], v[2:3], v[206:207]
	v_add_f32_dpp v22, v22, v22 quad_perm:[2,3,0,1] row_mask:0xf bank_mask:0xf bound_ctrl:1
	v_add_f32_dpp v42, v42, v42 quad_perm:[2,3,0,1] row_mask:0xf bank_mask:0xf bound_ctrl:1
	v_pk_mul_f32 v[12:13], v[0:1], v[224:225]
	v_add_f32_dpp v22, v22, v22 row_ror:4 row_mask:0xf bank_mask:0xf bound_ctrl:1
	v_add_f32_dpp v42, v42, v42 row_ror:4 row_mask:0xf bank_mask:0xf bound_ctrl:1
	v_pk_mul_f32 v[14:15], v[0:1], v[228:229]
	v_add_f32_dpp v240, v22, v22 row_ror:8 row_mask:0xf bank_mask:0xf bound_ctrl:1
	v_add_f32_dpp v42, v42, v42 row_ror:8 row_mask:0xf bank_mask:0xf bound_ctrl:1
	v_pk_fma_f32 v[8:9], v[240:241], v[212:213], v[8:9] op_sel:[1,0,0] op_sel_hi:[1,1,1]
	v_pk_fma_f32 v[10:11], v[240:241], v[214:215], v[10:11] op_sel:[1,0,0] op_sel_hi:[1,1,1]
	v_fma_f32 v4, v240, v232, v42
	v_pk_fma_f32 v[8:9], v[242:243], v[220:221], v[8:9] op_sel:[1,0,0] op_sel_hi:[1,1,1]
	v_fma_f32 v242, v241, v233, v4
	v_pk_fma_f32 v[10:11], v[242:243], v[222:223], v[10:11] op_sel:[1,0,0] op_sel_hi:[1,1,1]
	v_pk_fma_f32 v[12:13], v[2:3], v[226:227], v[12:13]
	v_pk_fma_f32 v[14:15], v[2:3], v[230:231], v[14:15]
	v_pk_fma_f32 v[0:1], v[240:241], v[208:209], v[8:9] op_sel:[0,0,0] op_sel_hi:[0,1,1]
	v_pk_fma_f32 v[2:3], v[240:241], v[210:211], v[10:11] op_sel:[0,0,0] op_sel_hi:[0,1,1]
	v_pk_fma_f32 v[0:1], v[242:243], v[216:217], v[0:1] op_sel:[0,0,0] op_sel_hi:[0,1,1]
	v_pk_fma_f32 v[2:3], v[242:243], v[218:219], v[2:3] op_sel:[0,0,0] op_sel_hi:[0,1,1]
	v_pk_fma_f32 v[12:13], v[240:241], v[234:235], v[12:13]
	v_pk_fma_f32 v[14:15], v[242:243], v[238:239], v[14:15]
	v_pk_fma_f32 v[14:15], v[240:241], v[236:237], v[14:15]
	v_add_f32_e32 v126, v12, v13
	v_add_f32_e32 v127, v14, v15
	ds_read_b128 v[196:199], v130 offset:12480
	ds_read_b128 v[200:203], v130 offset:12736
	ds_read_b128 v[204:207], v130 offset:12992
	ds_read_b128 v[208:211], v130 offset:13248
	ds_read_b128 v[212:215], v130 offset:13504
	ds_read_b128 v[216:219], v130 offset:13760
	ds_read_b128 v[220:223], v130 offset:14016
	ds_read_b128 v[224:227], v130 offset:14272
	ds_read_b128 v[228:231], v130 offset:14528
	ds_read_b128 v[232:235], v129 offset:14912
	ds_read_b128 v[236:239], v129 offset:14928
	ds_read_b32 v241, v128 offset:14784
	ds_read_b32 v243, v128 offset:14848
	ds_write2st64_b32 v131, v126, v127 offset0:180 offset1:184
	s_waitcnt lgkmcnt(14)
	v_pk_mul_f32 v[4:5], v[0:1], v[44:45]
	v_pk_mul_f32 v[6:7], v[0:1], v[48:49]
	v_pk_fma_f32 v[4:5], v[2:3], v[46:47], v[4:5]
	v_pk_fma_f32 v[6:7], v[2:3], v[50:51], v[6:7]
	v_add_f32_e32 v22, v4, v5
	v_add_f32_e32 v42, v6, v7
	v_pk_mul_f32 v[8:9], v[0:1], v[52:53]
	v_add_f32_dpp v22, v22, v22 quad_perm:[1,0,3,2] row_mask:0xf bank_mask:0xf bound_ctrl:1
	v_add_f32_dpp v42, v42, v42 quad_perm:[1,0,3,2] row_mask:0xf bank_mask:0xf bound_ctrl:1
	v_pk_mul_f32 v[10:11], v[2:3], v[54:55]
	v_add_f32_dpp v22, v22, v22 quad_perm:[2,3,0,1] row_mask:0xf bank_mask:0xf bound_ctrl:1
	v_add_f32_dpp v42, v42, v42 quad_perm:[2,3,0,1] row_mask:0xf bank_mask:0xf bound_ctrl:1
	v_pk_mul_f32 v[12:13], v[0:1], v[72:73]
	v_add_f32_dpp v22, v22, v22 row_ror:4 row_mask:0xf bank_mask:0xf bound_ctrl:1
	v_add_f32_dpp v42, v42, v42 row_ror:4 row_mask:0xf bank_mask:0xf bound_ctrl:1
	v_pk_mul_f32 v[14:15], v[0:1], v[76:77]
	v_add_f32_dpp v88, v22, v22 row_ror:8 row_mask:0xf bank_mask:0xf bound_ctrl:1
	v_add_f32_dpp v42, v42, v42 row_ror:8 row_mask:0xf bank_mask:0xf bound_ctrl:1
	v_pk_fma_f32 v[8:9], v[88:89], v[60:61], v[8:9] op_sel:[1,0,0] op_sel_hi:[1,1,1]
	v_pk_fma_f32 v[10:11], v[88:89], v[62:63], v[10:11] op_sel:[1,0,0] op_sel_hi:[1,1,1]
	v_fma_f32 v4, v88, v80, v42
	v_pk_fma_f32 v[8:9], v[90:91], v[68:69], v[8:9] op_sel:[1,0,0] op_sel_hi:[1,1,1]
	v_fma_f32 v90, v89, v81, v4
	v_pk_fma_f32 v[10:11], v[90:91], v[70:71], v[10:11] op_sel:[1,0,0] op_sel_hi:[1,1,1]
	v_pk_fma_f32 v[12:13], v[2:3], v[74:75], v[12:13]
	v_pk_fma_f32 v[14:15], v[2:3], v[78:79], v[14:15]
	v_pk_fma_f32 v[0:1], v[88:89], v[56:57], v[8:9] op_sel:[0,0,0] op_sel_hi:[0,1,1]
	v_pk_fma_f32 v[2:3], v[88:89], v[58:59], v[10:11] op_sel:[0,0,0] op_sel_hi:[0,1,1]
	v_pk_fma_f32 v[0:1], v[90:91], v[64:65], v[0:1] op_sel:[0,0,0] op_sel_hi:[0,1,1]
	v_pk_fma_f32 v[2:3], v[90:91], v[66:67], v[2:3] op_sel:[0,0,0] op_sel_hi:[0,1,1]
	v_pk_fma_f32 v[12:13], v[88:89], v[82:83], v[12:13]
	v_pk_fma_f32 v[14:15], v[90:91], v[86:87], v[14:15]
	v_pk_fma_f32 v[14:15], v[88:89], v[84:85], v[14:15]
	v_add_f32_e32 v126, v12, v13
	v_add_f32_e32 v127, v14, v15
	ds_read_b128 v[44:47], v130 offset:14976
	ds_read_b128 v[48:51], v130 offset:15232
	ds_read_b128 v[52:55], v130 offset:15488
	ds_read_b128 v[56:59], v130 offset:15744
	ds_read_b128 v[60:63], v130 offset:16000
	ds_read_b128 v[64:67], v130 offset:16256
	ds_read_b128 v[68:71], v130 offset:16512
	ds_read_b128 v[72:75], v130 offset:16768
	ds_read_b128 v[76:79], v130 offset:17024
	ds_read_b128 v[80:83], v129 offset:17408
	ds_read_b128 v[84:87], v129 offset:17424
	ds_read_b32 v89, v128 offset:17280
	ds_read_b32 v91, v128 offset:17344
	ds_write2st64_b32 v131, v126, v127 offset0:188 offset1:192
	s_waitcnt lgkmcnt(14)
	v_pk_mul_f32 v[4:5], v[0:1], v[196:197]
	v_pk_mul_f32 v[6:7], v[0:1], v[200:201]
	v_pk_fma_f32 v[4:5], v[2:3], v[198:199], v[4:5]
	v_pk_fma_f32 v[6:7], v[2:3], v[202:203], v[6:7]
	v_add_f32_e32 v22, v4, v5
	v_add_f32_e32 v42, v6, v7
	v_pk_mul_f32 v[8:9], v[0:1], v[204:205]
	v_add_f32_dpp v22, v22, v22 quad_perm:[1,0,3,2] row_mask:0xf bank_mask:0xf bound_ctrl:1
	v_add_f32_dpp v42, v42, v42 quad_perm:[1,0,3,2] row_mask:0xf bank_mask:0xf bound_ctrl:1
	v_pk_mul_f32 v[10:11], v[2:3], v[206:207]
	v_add_f32_dpp v22, v22, v22 quad_perm:[2,3,0,1] row_mask:0xf bank_mask:0xf bound_ctrl:1
	v_add_f32_dpp v42, v42, v42 quad_perm:[2,3,0,1] row_mask:0xf bank_mask:0xf bound_ctrl:1
	v_pk_mul_f32 v[12:13], v[0:1], v[224:225]
	v_add_f32_dpp v22, v22, v22 row_ror:4 row_mask:0xf bank_mask:0xf bound_ctrl:1
	v_add_f32_dpp v42, v42, v42 row_ror:4 row_mask:0xf bank_mask:0xf bound_ctrl:1
	v_pk_mul_f32 v[14:15], v[0:1], v[228:229]
	v_add_f32_dpp v240, v22, v22 row_ror:8 row_mask:0xf bank_mask:0xf bound_ctrl:1
	v_add_f32_dpp v42, v42, v42 row_ror:8 row_mask:0xf bank_mask:0xf bound_ctrl:1
	v_pk_fma_f32 v[8:9], v[240:241], v[212:213], v[8:9] op_sel:[1,0,0] op_sel_hi:[1,1,1]
	v_pk_fma_f32 v[10:11], v[240:241], v[214:215], v[10:11] op_sel:[1,0,0] op_sel_hi:[1,1,1]
	v_fma_f32 v4, v240, v232, v42
	v_pk_fma_f32 v[8:9], v[242:243], v[220:221], v[8:9] op_sel:[1,0,0] op_sel_hi:[1,1,1]
	v_fma_f32 v242, v241, v233, v4
	v_pk_fma_f32 v[10:11], v[242:243], v[222:223], v[10:11] op_sel:[1,0,0] op_sel_hi:[1,1,1]
	v_pk_fma_f32 v[12:13], v[2:3], v[226:227], v[12:13]
	v_pk_fma_f32 v[14:15], v[2:3], v[230:231], v[14:15]
	v_pk_fma_f32 v[0:1], v[240:241], v[208:209], v[8:9] op_sel:[0,0,0] op_sel_hi:[0,1,1]
	v_pk_fma_f32 v[2:3], v[240:241], v[210:211], v[10:11] op_sel:[0,0,0] op_sel_hi:[0,1,1]
	v_pk_fma_f32 v[0:1], v[242:243], v[216:217], v[0:1] op_sel:[0,0,0] op_sel_hi:[0,1,1]
	v_pk_fma_f32 v[2:3], v[242:243], v[218:219], v[2:3] op_sel:[0,0,0] op_sel_hi:[0,1,1]
	v_pk_fma_f32 v[12:13], v[240:241], v[234:235], v[12:13]
	v_pk_fma_f32 v[14:15], v[242:243], v[238:239], v[14:15]
	v_pk_fma_f32 v[14:15], v[240:241], v[236:237], v[14:15]
	v_add_f32_e32 v126, v12, v13
	v_add_f32_e32 v127, v14, v15
	ds_read_b128 v[196:199], v130 offset:17472
	ds_read_b128 v[200:203], v130 offset:17728
	ds_read_b128 v[204:207], v130 offset:17984
	ds_read_b128 v[208:211], v130 offset:18240
	ds_read_b128 v[212:215], v130 offset:18496
	ds_read_b128 v[216:219], v130 offset:18752
	ds_read_b128 v[220:223], v130 offset:19008
	ds_read_b128 v[224:227], v130 offset:19264
	ds_read_b128 v[228:231], v130 offset:19520
	ds_read_b128 v[232:235], v129 offset:19904
	ds_read_b128 v[236:239], v129 offset:19920
	ds_read_b32 v241, v128 offset:19776
	ds_read_b32 v243, v128 offset:19840
	ds_write2st64_b32 v131, v126, v127 offset0:196 offset1:200
	s_waitcnt lgkmcnt(14)
	v_pk_mul_f32 v[4:5], v[0:1], v[44:45]
	v_pk_mul_f32 v[6:7], v[0:1], v[48:49]
	v_pk_fma_f32 v[4:5], v[2:3], v[46:47], v[4:5]
	v_pk_fma_f32 v[6:7], v[2:3], v[50:51], v[6:7]
	v_add_f32_e32 v22, v4, v5
	v_add_f32_e32 v42, v6, v7
	v_pk_mul_f32 v[8:9], v[0:1], v[52:53]
	v_add_f32_dpp v22, v22, v22 quad_perm:[1,0,3,2] row_mask:0xf bank_mask:0xf bound_ctrl:1
	v_add_f32_dpp v42, v42, v42 quad_perm:[1,0,3,2] row_mask:0xf bank_mask:0xf bound_ctrl:1
	v_pk_mul_f32 v[10:11], v[2:3], v[54:55]
	v_add_f32_dpp v22, v22, v22 quad_perm:[2,3,0,1] row_mask:0xf bank_mask:0xf bound_ctrl:1
	v_add_f32_dpp v42, v42, v42 quad_perm:[2,3,0,1] row_mask:0xf bank_mask:0xf bound_ctrl:1
	v_pk_mul_f32 v[12:13], v[0:1], v[72:73]
	v_add_f32_dpp v22, v22, v22 row_ror:4 row_mask:0xf bank_mask:0xf bound_ctrl:1
	v_add_f32_dpp v42, v42, v42 row_ror:4 row_mask:0xf bank_mask:0xf bound_ctrl:1
	v_pk_mul_f32 v[14:15], v[0:1], v[76:77]
	v_add_f32_dpp v88, v22, v22 row_ror:8 row_mask:0xf bank_mask:0xf bound_ctrl:1
	v_add_f32_dpp v42, v42, v42 row_ror:8 row_mask:0xf bank_mask:0xf bound_ctrl:1
	v_pk_fma_f32 v[8:9], v[88:89], v[60:61], v[8:9] op_sel:[1,0,0] op_sel_hi:[1,1,1]
	v_pk_fma_f32 v[10:11], v[88:89], v[62:63], v[10:11] op_sel:[1,0,0] op_sel_hi:[1,1,1]
	v_fma_f32 v4, v88, v80, v42
	v_pk_fma_f32 v[8:9], v[90:91], v[68:69], v[8:9] op_sel:[1,0,0] op_sel_hi:[1,1,1]
	v_fma_f32 v90, v89, v81, v4
	v_pk_fma_f32 v[10:11], v[90:91], v[70:71], v[10:11] op_sel:[1,0,0] op_sel_hi:[1,1,1]
	v_pk_fma_f32 v[12:13], v[2:3], v[74:75], v[12:13]
	v_pk_fma_f32 v[14:15], v[2:3], v[78:79], v[14:15]
	v_pk_fma_f32 v[0:1], v[88:89], v[56:57], v[8:9] op_sel:[0,0,0] op_sel_hi:[0,1,1]
	v_pk_fma_f32 v[2:3], v[88:89], v[58:59], v[10:11] op_sel:[0,0,0] op_sel_hi:[0,1,1]
	v_pk_fma_f32 v[0:1], v[90:91], v[64:65], v[0:1] op_sel:[0,0,0] op_sel_hi:[0,1,1]
	v_pk_fma_f32 v[2:3], v[90:91], v[66:67], v[2:3] op_sel:[0,0,0] op_sel_hi:[0,1,1]
	v_pk_fma_f32 v[12:13], v[88:89], v[82:83], v[12:13]
	v_pk_fma_f32 v[14:15], v[90:91], v[86:87], v[14:15]
	v_pk_fma_f32 v[14:15], v[88:89], v[84:85], v[14:15]
	v_add_f32_e32 v126, v12, v13
	v_add_f32_e32 v127, v14, v15
	ds_write2st64_b32 v131, v126, v127 offset0:204 offset1:208
	s_waitcnt lgkmcnt(1)
	v_pk_mul_f32 v[4:5], v[0:1], v[196:197]
	v_pk_mul_f32 v[6:7], v[0:1], v[200:201]
	v_pk_fma_f32 v[4:5], v[2:3], v[198:199], v[4:5]
	v_pk_fma_f32 v[6:7], v[2:3], v[202:203], v[6:7]
	v_add_f32_e32 v22, v4, v5
	v_add_f32_e32 v42, v6, v7
	v_pk_mul_f32 v[8:9], v[0:1], v[204:205]
	v_add_f32_dpp v22, v22, v22 quad_perm:[1,0,3,2] row_mask:0xf bank_mask:0xf bound_ctrl:1
	v_add_f32_dpp v42, v42, v42 quad_perm:[1,0,3,2] row_mask:0xf bank_mask:0xf bound_ctrl:1
	v_pk_mul_f32 v[10:11], v[2:3], v[206:207]
	v_add_f32_dpp v22, v22, v22 quad_perm:[2,3,0,1] row_mask:0xf bank_mask:0xf bound_ctrl:1
	v_add_f32_dpp v42, v42, v42 quad_perm:[2,3,0,1] row_mask:0xf bank_mask:0xf bound_ctrl:1
	v_pk_mul_f32 v[12:13], v[0:1], v[224:225]
	v_add_f32_dpp v22, v22, v22 row_ror:4 row_mask:0xf bank_mask:0xf bound_ctrl:1
	v_add_f32_dpp v42, v42, v42 row_ror:4 row_mask:0xf bank_mask:0xf bound_ctrl:1
	v_pk_mul_f32 v[14:15], v[0:1], v[228:229]
	v_add_f32_dpp v240, v22, v22 row_ror:8 row_mask:0xf bank_mask:0xf bound_ctrl:1
	v_add_f32_dpp v42, v42, v42 row_ror:8 row_mask:0xf bank_mask:0xf bound_ctrl:1
	v_pk_fma_f32 v[8:9], v[240:241], v[212:213], v[8:9] op_sel:[1,0,0] op_sel_hi:[1,1,1]
	v_pk_fma_f32 v[10:11], v[240:241], v[214:215], v[10:11] op_sel:[1,0,0] op_sel_hi:[1,1,1]
	v_fma_f32 v4, v240, v232, v42
	v_pk_fma_f32 v[8:9], v[242:243], v[220:221], v[8:9] op_sel:[1,0,0] op_sel_hi:[1,1,1]
	v_fma_f32 v242, v241, v233, v4
	v_pk_fma_f32 v[10:11], v[242:243], v[222:223], v[10:11] op_sel:[1,0,0] op_sel_hi:[1,1,1]
	v_pk_fma_f32 v[12:13], v[2:3], v[226:227], v[12:13]
	v_pk_fma_f32 v[14:15], v[2:3], v[230:231], v[14:15]
	v_pk_fma_f32 v[0:1], v[240:241], v[208:209], v[8:9] op_sel:[0,0,0] op_sel_hi:[0,1,1]
	v_pk_fma_f32 v[2:3], v[240:241], v[210:211], v[10:11] op_sel:[0,0,0] op_sel_hi:[0,1,1]
	v_pk_fma_f32 v[0:1], v[242:243], v[216:217], v[0:1] op_sel:[0,0,0] op_sel_hi:[0,1,1]
	v_pk_fma_f32 v[2:3], v[242:243], v[218:219], v[2:3] op_sel:[0,0,0] op_sel_hi:[0,1,1]
	v_pk_fma_f32 v[12:13], v[240:241], v[234:235], v[12:13]
	v_pk_fma_f32 v[14:15], v[242:243], v[238:239], v[14:15]
	v_pk_fma_f32 v[14:15], v[240:241], v[236:237], v[14:15]
	v_add_f32_e32 v126, v12, v13
	v_add_f32_e32 v127, v14, v15
	ds_write2st64_b32 v131, v126, v127 offset0:212 offset1:216
